# phase-8 static priority: s_setprio 2 at v-side (memory-bound gather) entry so drifted gather waves issue loads ahead of dot-bound u-side waves
# speedup vs baseline: 1.0090x; 1.0090x over previous
; __device__ void phase_gather(const Params& p) {
;   const int tid = threadIdx.x, lane = tid & 63, wid = tid >> 6;
;   unsigned char* ws = p.ws;
;   const unsigned char* ub = ws + OFF_XB;
;   const unsigned char* vb = ws + OFF_XB + 16 * MIB;
;   const float* scales = (const float*)(ws + OFF_SCALES);
;   const int* idxg = (const int*)(ws + OFF_IDX);
;   const float* gg = (const float*)(ws + OFF_G);
;   const float* ssq2 = (const float*)(ws + OFF_SSQ2);
;   const bool b5 = (lane & 32) != 0, b4 = (lane & 16) != 0, b3 = (lane & 8) != 0;
;   const int srcl = ((lane & 1) << 3) | (((lane >> 1) & 1) << 4) | (((lane >> 2) & 1) << 5);
;   for (int t = blockIdx.x * 8 + wid; t < T_TOK; t += gridDim.x * 8) {
;     const int id0 = idxg[(size_t)t * 128 + lane], id1 = idxg[(size_t)t * 128 + 64 + lane];
;     const float g0 = gg[(size_t)t * 128 + lane], g1 = gg[(size_t)t * 128 + 64 + lane];
;     const float su0 = scales[id0], su1 = scales[id1], sv0 = scales[16384 + id0], sv1 = scales[16384 + id1];
;     float* orow = p.out + (size_t)t * DM + lane * 32;
;     const float sx = ((const float*)(ws + OFF_WBUF + 8 * MIB))[t];
;     float sq = (lane < 32) ? ssq2[(size_t)t * 32 + lane] : 0.f;
;     sq = wave_sum(sq);
;     const float rs2 = rsqrtf(sq * (1.f / 2048.f) + EPSV);
;     const int* wbuf = (const int*)(ws + OFF_WBUF);
.LBB0_1316:
	s_waitcnt vmcnt(0)
	s_setprio 2
	s_and_saveexec_b64 s[2:3], s[0:1]
	s_cbranch_execz .LBB0_1323
	s_add_u32 s0, s34, 0x1dc90000
	s_addc_u32 s1, s35, 0
	v_writelane_b32 v250, s0, 20
	v_lshlrev_b32_e32 v0, 2, v138
	v_mov_b32_e32 v1, 0
	v_writelane_b32 v250, s1, 21
	s_add_u32 s0, s34, 0xc800000
	s_addc_u32 s1, s35, 0
	v_writelane_b32 v250, s0, 22
	v_cmp_lt_i32_e32 vcc, v89, v84
	v_lshl_add_u64 v[2:3], s[34:35], 0, v[0:1]
	v_writelane_b32 v250, s1, 23
	s_add_u32 s0, s34, 0x17c00000
	s_addc_u32 s1, s35, 0
	v_cndmask_b32_e32 v0, v83, v89, vcc
	v_cmp_lt_i32_e32 vcc, v90, v84
	v_writelane_b32 v250, s0, 24
	v_lshlrev_b32_e32 v126, 2, v0
	v_cndmask_b32_e32 v0, v83, v90, vcc
	v_cmp_lt_i32_e32 vcc, v88, v84
	v_writelane_b32 v250, s1, 25
	v_cmp_gt_u32_e64 s[0:1], 32, v138
	v_lshlrev_b32_e32 v127, 2, v0
	v_cndmask_b32_e32 v0, v83, v88, vcc
	v_cmp_lt_i32_e32 vcc, v87, v84
	v_writelane_b32 v250, s0, 26
	v_lshlrev_b32_e32 v128, 2, v0
	v_cndmask_b32_e32 v0, v83, v87, vcc
	v_cmp_lt_i32_e32 vcc, v86, v84
	v_writelane_b32 v250, s1, 27
	v_lshlrev_b32_e32 v129, 2, v0
	v_cndmask_b32_e32 v0, v83, v86, vcc
	v_cmp_lt_i32_e32 vcc, v85, v84
	s_mov_b64 s[0:1], 0x1da90000
	v_lshlrev_b32_e32 v130, 2, v0
	v_cndmask_b32_e32 v0, v83, v85, vcc
	v_writelane_b32 v250, s68, 28
	v_lshl_add_u64 v[114:115], v[2:3], 0, s[0:1]
	v_lshlrev_b32_e32 v131, 2, v0
	s_mov_b64 s[0:1], 0x1000000
	v_lshlrev_b32_e32 v0, 7, v138
	v_writelane_b32 v250, s69, 29
	v_and_b32_e32 v132, 24, v82
	v_lshl_add_u64 v[116:117], v[72:73], 0, s[0:1]
	v_lshl_add_u64 v[118:119], s[30:31], 0, v[0:1]
	v_lshl_add_u64 v[120:121], s[28:29], 0, v[0:1]
	global_load_dwordx4 v[188:191], v[120:121], off offset:16
	global_load_dwordx4 v[192:195], v[120:121], off offset:32
	global_load_dwordx4 v[196:199], v[120:121], off offset:48
	global_load_dwordx4 v[200:203], v[120:121], off offset:64
	global_load_dwordx4 v[204:207], v[120:121], off offset:80
	global_load_dwordx4 v[208:211], v[120:121], off offset:96
	global_load_dwordx4 v[212:215], v[120:121], off offset:112
	s_mov_b64 s[0:1], 0
	v_mov_b32_e32 v133, 0x358637bd
	s_mov_b32 s55, 0x800000
	s_mov_b32 s33, 0x5010400
	s_mov_b32 s52, 0x7030602
	s_mov_b32 s53, 0x5040100
	s_mov_b32 s54, 0x7060302
	v_writelane_b32 v250, s70, 30
	s_nop 1
	v_writelane_b32 v250, s71, 31
